# gla_scan prefix sums via DPP row_shr/row_bcast instead of 7 ds_bpermute rounds
# speedup vs baseline: 1.0311x; 1.0032x over previous
; DI bf16_t f2bf(float x) { return (bf16_t)(pk2(x, 0.f) & 0xffffu); }
; DI float bf2f(unsigned x) { return __uint_as_float(x << 16); }
;     ...
;             float cum[2];
; #pragma unroll
;             for (int e = 0; e < 2; ++e) {
;                 float z = bb[e];
; #pragma unroll
;                 for (int q = 0; q < 4; ++q) { z += a4[q].x * wa[e][4 * q] + a4[q].y * wa[e][4 * q + 1] + a4[q].z * wa[e][4 * q + 2] + a4[q].w * wa[e][4 * q + 3]; }
;                 cum[e] = (fminf(z, 0.f) - __logf(1.f + __expf(-fabsf(z)))) * (1.f / 16.f);
;             }
; #pragma unroll
;             for (int o = 1; o < 64; o <<= 1) {
;                 const float t0 = __shfl_up(cum[0], o), t1 = __shfl_up(cum[1], o);
;                 if (l >= o) { cum[0] += t0; cum[1] += t1; }
;             }
;             const float tot0 = __shfl(cum[0], 63), tot1 = __shfl(cum[1], 63);
;             kdl[(buf * 16 + 2 * w) * 64 + l] = f2bf(bf2f(kraw & 0xffffu) * __expf(tot0 - cum[0]));
;             kdl[(buf * 16 + 2 * w + 1) * 64 + l] = f2bf(bf2f(kraw >> 16) * __expf(tot1 - cum[1]));
;             if (l == 0) { decl[buf * 16 + 2 * w] = __expf(tot0); decl[buf * 16 + 2 * w + 1] = __expf(tot1); }
.LBB0_419:
	s_waitcnt vmcnt(5)
	v_mov_b32_e32 v175, v60
	v_mov_b32_e32 v60, v69
	v_mov_b32_e32 v174, v68
	v_pk_mul_f32 v[16:17], v[152:153], v[60:61]
	v_mov_b32_e32 v68, v70
	v_pk_fma_f32 v[16:17], v[150:151], v[174:175], v[16:17]
	v_mov_b32_e32 v69, v62
	v_pk_fma_f32 v[16:17], v[148:149], v[68:69], v[16:17]
	v_mov_b32_e32 v62, v71
	v_pk_fma_f32 v[16:17], v[146:147], v[62:63], v[16:17]
	v_mov_b32_e32 v71, v56
	v_add_f32_e32 v17, v112, v17
	v_mov_b32_e32 v56, v65
	v_add_f32_e32 v18, v16, v17
	v_mov_b32_e32 v70, v64
	v_pk_mul_f32 v[16:17], v[144:145], v[56:57]
	v_mov_b32_e32 v64, v66
	v_pk_fma_f32 v[16:17], v[142:143], v[70:71], v[16:17]
	v_mov_b32_e32 v65, v58
	v_pk_fma_f32 v[16:17], v[140:141], v[64:65], v[16:17]
	v_mov_b32_e32 v58, v67
	s_waitcnt vmcnt(4)
	v_mov_b32_e32 v173, v159
	v_ashrrev_i32_e32 v159, 31, v158
	v_readlane_b32 s20, v253, 13
	v_pk_fma_f32 v[16:17], v[138:139], v[58:59], v[16:17]
	v_lshlrev_b64 v[8:9], 6, v[158:159]
	v_readlane_b32 s21, v253, 14
	v_add_f32_e32 v17, v17, v18
	v_add_f32_e32 v66, v16, v17
	v_lshl_add_u64 v[8:9], s[20:21], 0, v[8:9]
	s_mov_b32 s20, 0xbfb8aa3b
	v_mul_f32_e64 v16, |v66|, s20
	v_lshl_add_u64 v[10:11], v[156:157], 0, s[34:35]
	s_mov_b32 s21, 0x14800000
	v_exp_f32_e32 v16, v16
	v_add_co_u32_e64 v12, s[50:51], s21, v10
	v_lshl_add_u64 v[14:15], v[154:155], 0, s[34:35]
	s_nop 0
	v_addc_co_u32_e64 v13, s[50:51], 0, v11, s[50:51]
	v_pk_mul_f32 v[60:61], v[136:137], v[60:61]
	v_add_co_u32_e64 v14, s[50:51], s21, v14
	v_pk_fma_f32 v[60:61], v[134:135], v[174:175], v[60:61]
	s_nop 0
	v_addc_co_u32_e64 v15, s[50:51], 0, v15, s[50:51]
	v_add_f32_e32 v16, 1.0, v16
	s_mov_b32 s21, 0x800000
	v_pk_fma_f32 v[60:61], v[132:133], v[68:69], v[60:61]
	v_pk_mul_f32 v[56:57], v[128:129], v[56:57]
	v_cmp_gt_f32_e64 s[50:51], s21, v16
	v_pk_fma_f32 v[60:61], v[130:131], v[62:63], v[60:61]
	v_pk_fma_f32 v[56:57], v[126:127], v[70:71], v[56:57]
	global_load_dwordx4 v[24:27], v[8:9], off offset:48
	global_load_dwordx4 v[48:51], v[8:9], off offset:32
	global_load_dwordx4 v[28:31], v[8:9], off offset:16
	global_load_dwordx4 v[52:55], v[8:9], off
	v_lshlrev_b64 v[8:9], 10, v[158:159]
	v_cndmask_b32_e64 v17, 0, 32, s[50:51]
	v_add_f32_e32 v61, v113, v61
	v_pk_fma_f32 v[56:57], v[124:125], v[64:65], v[56:57]
	v_lshl_add_u64 v[8:9], v[120:121], 0, v[8:9]
	v_ldexp_f32 v16, v16, v17
	v_add_f32_e32 v60, v60, v61
	v_pk_fma_f32 v[56:57], v[122:123], v[58:59], v[56:57]
	global_load_dword v159, v[8:9], off
	s_nop 0
	global_load_dwordx4 v[8:11], v[12:13], off offset:128
	v_log_f32_e32 v67, v16
	global_load_dwordx4 v[16:19], v[12:13], off offset:192
	global_load_dwordx4 v[20:23], v[14:15], off offset:128
	s_nop 0
	global_load_dwordx4 v[12:15], v[14:15], off offset:192
	v_add_f32_e32 v57, v57, v60
	v_add_f32_e32 v57, v56, v57
	v_mul_f32_e64 v56, |v57|, s20
	v_exp_f32_e32 v56, v56
	v_mul_f32_e32 v178, 0x3f317217, v67
	s_mov_b32 s27, 0x3f317217
	v_fma_f32 v178, v67, s27, -v178
	v_fmac_f32_e32 v178, 0x3377d1cf, v67
	s_mov_b32 s20, 0x7f800000
	v_fmac_f32_e32 v178, 0x3f317217, v67
	v_cmp_lt_f32_e64 s[52:53], |v67|, s20
	v_add_f32_e32 v56, 1.0, v56
	v_min_f32_e32 v66, 0, v66
	v_cndmask_b32_e64 v58, v67, v178, s[52:53]
	v_cmp_gt_f32_e64 s[52:53], s21, v56
	v_min_f32_e32 v67, 0, v57
	s_nop 0
	v_cndmask_b32_e64 v59, 0, 32, s[52:53]
	v_ldexp_f32 v56, v56, v59
	v_log_f32_e32 v59, v56
	v_cndmask_b32_e64 v56, 0, v219, s[50:51]
	v_sub_f32_e32 v56, v58, v56
	v_cndmask_b32_e64 v58, 0, v219, s[52:53]
	v_mul_f32_e32 v57, 0x3f317217, v59
	v_fma_f32 v57, v59, s27, -v57
	v_fmac_f32_e32 v57, 0x3377d1cf, v59
	v_fmac_f32_e32 v57, 0x3f317217, v59
	v_cmp_lt_f32_e64 s[50:51], |v59|, s20
	s_and_b32 s27, s59, 16
	s_nop 0
	v_cndmask_b32_e64 v57, v59, v57, s[50:51]
	v_sub_f32_e32 v57, v57, v58
	v_pk_add_f32 v[56:57], v[66:67], v[56:57] neg_lo:[0,1] neg_hi:[0,1]
	s_nop 0
	v_pk_mul_f32 v[58:59], v[56:57], s[12:13] op_sel_hi:[1,0]
	v_lshlrev_b32_e32 v60, 16, v173
	s_nop 0
	v_add_f32_dpp v58, v58, v58 row_shr:1 row_mask:0xf bank_mask:0xf
	v_add_f32_dpp v59, v59, v59 row_shr:1 row_mask:0xf bank_mask:0xf
	s_nop 0
	v_add_f32_dpp v58, v58, v58 row_shr:2 row_mask:0xf bank_mask:0xf
	v_add_f32_dpp v59, v59, v59 row_shr:2 row_mask:0xf bank_mask:0xf
	s_nop 0
	v_add_f32_dpp v58, v58, v58 row_shr:4 row_mask:0xf bank_mask:0xf
	v_add_f32_dpp v59, v59, v59 row_shr:4 row_mask:0xf bank_mask:0xf
	s_nop 0
	v_add_f32_dpp v58, v58, v58 row_shr:8 row_mask:0xf bank_mask:0xf
	v_add_f32_dpp v59, v59, v59 row_shr:8 row_mask:0xf bank_mask:0xf
	s_nop 0
	v_add_f32_dpp v58, v58, v58 row_bcast:15 row_mask:0xa bank_mask:0xf
	v_add_f32_dpp v59, v59, v59 row_bcast:15 row_mask:0xa bank_mask:0xf
	s_nop 0
	v_add_f32_dpp v58, v58, v58 row_bcast:31 row_mask:0xc bank_mask:0xf
	v_add_f32_dpp v59, v59, v59 row_bcast:31 row_mask:0xc bank_mask:0xf
	s_nop 0
	v_readlane_b32 s98, v58, 63
	v_readlane_b32 s99, v59, 63
	s_nop 1
	v_mov_b32_e32 v56, s98
	v_mov_b32_e32 v57, s99
	s_waitcnt lgkmcnt(1)
	v_sub_f32_e32 v58, v56, v58
	v_mul_f32_e32 v58, 0x3fb8aa3b, v58
	v_exp_f32_e32 v58, v58
	s_waitcnt lgkmcnt(0)
	v_sub_f32_e32 v59, v57, v59
	v_mul_f32_e32 v59, 0x3fb8aa3b, v59
	v_exp_f32_e32 v59, v59
	v_mul_f32_e32 v58, v58, v60
	v_cvt_pk_bf16_f32 v58, v58, s0
	v_lshl_add_u32 v60, s27, 7, v172
	ds_write_b16 v60, v58
	v_and_b32_e32 v58, 0xffff0000, v173
	v_mul_f32_e32 v58, v59, v58
	v_cvt_pk_bf16_f32 v58, v58, s0
	ds_write_b16 v60, v58 offset:128
	s_and_saveexec_b64 s[20:21], vcc
	s_cbranch_execz .LBB0_421
	v_mul_f32_e32 v56, 0x3fb8aa3b, v56
	v_mul_f32_e32 v57, 0x3fb8aa3b, v57
	v_exp_f32_e32 v56, v56
	v_exp_f32_e32 v57, v57
	v_lshl_add_u32 v58, s27, 2, v163
	ds_write_b64 v58, v[56:57] offset:4096

; DI bf16_t f2bf(float x) { return (bf16_t)(pk2(x, 0.f) & 0xffffu); }
; DI float bf2f(unsigned x) { return __uint_as_float(x << 16); }
;     ...
;             float cum[2];
; #pragma unroll
;             for (int e = 0; e < 2; ++e) {
;                 float z = bb[e];
; #pragma unroll
;                 for (int q = 0; q < 4; ++q) { z += a4[q].x * wa[e][4 * q] + a4[q].y * wa[e][4 * q + 1] + a4[q].z * wa[e][4 * q + 2] + a4[q].w * wa[e][4 * q + 3]; }
;                 cum[e] = (fminf(z, 0.f) - __logf(1.f + __expf(-fabsf(z)))) * (1.f / 16.f);
;             }
; #pragma unroll
;             for (int o = 1; o < 64; o <<= 1) {
;                 const float t0 = __shfl_up(cum[0], o), t1 = __shfl_up(cum[1], o);
;                 if (l >= o) { cum[0] += t0; cum[1] += t1; }
;             }
;             const float tot0 = __shfl(cum[0], 63), tot1 = __shfl(cum[1], 63);
;             kdl[(buf * 16 + 2 * w) * 64 + l] = f2bf(bf2f(kraw & 0xffffu) * __expf(tot0 - cum[0]));
;             kdl[(buf * 16 + 2 * w + 1) * 64 + l] = f2bf(bf2f(kraw >> 16) * __expf(tot1 - cum[1]));
;             if (l == 0) { decl[buf * 16 + 2 * w] = __expf(tot0); decl[buf * 16 + 2 * w + 1] = __expf(tot1); }
.LBB0_423:
	s_waitcnt vmcnt(8)
	v_mov_b32_e32 v35, v28
	v_mov_b32_e32 v36, v116
	v_mov_b32_e32 v37, v92
	s_waitcnt vmcnt(7)
	v_mov_b32_e32 v28, v53
	v_mov_b32_e32 v32, v118
	v_mov_b32_e32 v33, v86
	v_mov_b32_e32 v34, v52
	v_pk_mul_f32 v[36:37], v[36:37], v[28:29]
	v_mov_b32_e32 v38, v54
	v_pk_fma_f32 v[32:33], v[32:33], v[34:35], v[36:37]
	v_mov_b32_e32 v36, v108
	v_mov_b32_e32 v37, v90
	v_mov_b32_e32 v39, v30
	v_pk_fma_f32 v[32:33], v[36:37], v[38:39], v[32:33]
	v_mov_b32_e32 v36, v114
	v_mov_b32_e32 v37, v110
	v_mov_b32_e32 v30, v55
	v_pk_fma_f32 v[32:33], v[36:37], v[30:31], v[32:33]
	v_mov_b32_e32 v37, v24
	v_add_f32_e32 v32, v112, v32
	v_mov_b32_e32 v40, v104
	v_mov_b32_e32 v41, v106
	v_mov_b32_e32 v24, v49
	v_add_f32_e32 v44, v32, v33
	v_mov_b32_e32 v32, v88
	v_mov_b32_e32 v33, v102
	v_mov_b32_e32 v36, v48
	v_pk_mul_f32 v[40:41], v[40:41], v[24:25]
	v_mov_b32_e32 v42, v50
	v_pk_fma_f32 v[32:33], v[32:33], v[36:37], v[40:41]
	v_mov_b32_e32 v40, v100
	v_mov_b32_e32 v41, v98
	v_mov_b32_e32 v43, v26
	v_pk_fma_f32 v[32:33], v[40:41], v[42:43], v[32:33]
	v_mov_b32_e32 v40, v94
	v_mov_b32_e32 v41, v96
	v_mov_b32_e32 v26, v51
	v_pk_fma_f32 v[32:33], v[40:41], v[26:27], v[32:33]
	s_mov_b32 s20, 0xbfb8aa3b
	v_add_f32_e32 v32, v44, v32
	v_add_f32_e32 v32, v32, v33
	v_mul_f32_e64 v33, |v32|, s20
	v_exp_f32_e32 v33, v33
	v_mov_b32_e32 v92, v117
	v_mov_b32_e32 v86, v119
	v_pk_mul_f32 v[28:29], v[92:93], v[28:29]
	v_mov_b32_e32 v90, v109
	v_pk_fma_f32 v[28:29], v[86:87], v[34:35], v[28:29]
	v_mov_b32_e32 v106, v105
	v_add_f32_e32 v33, 1.0, v33
	s_mov_b32 s21, 0x800000
	v_pk_fma_f32 v[28:29], v[90:91], v[38:39], v[28:29]
	v_mov_b32_e32 v110, v115
	v_mov_b32_e32 v102, v89
	v_pk_mul_f32 v[24:25], v[106:107], v[24:25]
	v_cmp_gt_f32_e64 s[50:51], s21, v33
	v_pk_fma_f32 v[28:29], v[110:111], v[30:31], v[28:29]
	v_pk_fma_f32 v[24:25], v[102:103], v[36:37], v[24:25]
	v_mov_b32_e32 v98, v101
	v_cndmask_b32_e64 v40, 0, 32, s[50:51]
	v_add_f32_e32 v28, v113, v28
	v_pk_fma_f32 v[24:25], v[98:99], v[42:43], v[24:25]
	v_mov_b32_e32 v96, v95
	v_ldexp_f32 v33, v33, v40
	v_add_f32_e32 v28, v28, v29
	v_pk_fma_f32 v[24:25], v[96:97], v[26:27], v[24:25]
	v_log_f32_e32 v33, v33
	v_add_f32_e32 v24, v28, v24
	v_add_f32_e32 v25, v24, v25
	v_mul_f32_e64 v24, |v25|, s20
	v_exp_f32_e32 v24, v24
	v_mul_f32_e32 v40, 0x3f317217, v33
	s_mov_b32 s26, 0x3f317217
	v_fma_f32 v40, v33, s26, -v40
	v_fmac_f32_e32 v40, 0x3377d1cf, v33
	s_mov_b32 s20, 0x7f800000
	v_fmac_f32_e32 v40, 0x3f317217, v33
	v_cmp_lt_f32_e64 s[52:53], |v33|, s20
	v_add_f32_e32 v24, 1.0, v24
	v_min_f32_e32 v32, 0, v32
	v_cndmask_b32_e64 v26, v33, v40, s[52:53]
	v_cmp_gt_f32_e64 s[52:53], s21, v24
	v_min_f32_e32 v33, 0, v25
	s_nop 0
	v_cndmask_b32_e64 v27, 0, 32, s[52:53]
	v_ldexp_f32 v24, v24, v27
	v_log_f32_e32 v27, v24
	v_cndmask_b32_e64 v24, 0, v219, s[50:51]
	v_sub_f32_e32 v24, v26, v24
	v_cndmask_b32_e64 v26, 0, v219, s[52:53]
	v_mul_f32_e32 v25, 0x3f317217, v27
	v_fma_f32 v25, v27, s26, -v25
	v_fmac_f32_e32 v25, 0x3377d1cf, v27
	v_fmac_f32_e32 v25, 0x3f317217, v27
	v_cmp_lt_f32_e64 s[50:51], |v27|, s20
	s_nop 1
	v_cndmask_b32_e64 v25, v27, v25, s[50:51]
	v_sub_f32_e32 v25, v25, v26
	v_pk_add_f32 v[24:25], v[32:33], v[24:25] neg_lo:[0,1] neg_hi:[0,1]
	s_nop 0
	v_pk_mul_f32 v[26:27], v[24:25], s[12:13] op_sel_hi:[1,0]
	s_waitcnt vmcnt(6)
	v_lshlrev_b32_e32 v28, 16, v159
	s_nop 0
	v_add_f32_dpp v26, v26, v26 row_shr:1 row_mask:0xf bank_mask:0xf
	v_add_f32_dpp v27, v27, v27 row_shr:1 row_mask:0xf bank_mask:0xf
	s_nop 0
	v_add_f32_dpp v26, v26, v26 row_shr:2 row_mask:0xf bank_mask:0xf
	v_add_f32_dpp v27, v27, v27 row_shr:2 row_mask:0xf bank_mask:0xf
	s_nop 0
	v_add_f32_dpp v26, v26, v26 row_shr:4 row_mask:0xf bank_mask:0xf
	v_add_f32_dpp v27, v27, v27 row_shr:4 row_mask:0xf bank_mask:0xf
	s_nop 0
	v_add_f32_dpp v26, v26, v26 row_shr:8 row_mask:0xf bank_mask:0xf
	v_add_f32_dpp v27, v27, v27 row_shr:8 row_mask:0xf bank_mask:0xf
	s_nop 0
	v_add_f32_dpp v26, v26, v26 row_bcast:15 row_mask:0xa bank_mask:0xf
	v_add_f32_dpp v27, v27, v27 row_bcast:15 row_mask:0xa bank_mask:0xf
	s_nop 0
	v_add_f32_dpp v26, v26, v26 row_bcast:31 row_mask:0xc bank_mask:0xf
	v_add_f32_dpp v27, v27, v27 row_bcast:31 row_mask:0xc bank_mask:0xf
	s_nop 0
	v_readlane_b32 s98, v26, 63
	v_readlane_b32 s99, v27, 63
	s_nop 1
	v_mov_b32_e32 v24, s98
	v_mov_b32_e32 v25, s99
	s_waitcnt lgkmcnt(1)
	v_sub_f32_e32 v26, v24, v26
	v_mul_f32_e32 v26, 0x3fb8aa3b, v26
	v_exp_f32_e32 v26, v26
	s_waitcnt lgkmcnt(0)
	v_sub_f32_e32 v27, v25, v27
	v_mul_f32_e32 v27, 0x3fb8aa3b, v27
	v_exp_f32_e32 v27, v27
	v_mul_f32_e32 v26, v26, v28
	v_cvt_pk_bf16_f32 v26, v26, s0
	ds_write_b16 v172, v26 offset:2048
	v_and_b32_e32 v26, 0xffff0000, v159
	v_mul_f32_e32 v26, v27, v26
	v_cvt_pk_bf16_f32 v26, v26, s0
	ds_write_b16 v172, v26 offset:2176
	s_and_saveexec_b64 s[20:21], vcc
	s_cbranch_execz .LBB0_417
	v_mul_f32_e32 v24, 0x3fb8aa3b, v24
	v_mul_f32_e32 v25, 0x3fb8aa3b, v25
	v_exp_f32_e32 v24, v24
	v_exp_f32_e32 v25, v25
	ds_write_b64 v163, v[24:25] offset:4160
	s_branch .LBB0_417
